# GQA item prologue: first wait counted (vmcnt 23) instead of vmcnt(0), no longer drains previous item's stores
# baseline (speedup 1.0000x reference)
.LBB0_282:
	s_and_b32 s11, s22, 7
	s_mul_hi_i32 s9, s8, 0x1400
	s_mulk_i32 s8, 0x1400
	s_add_u32 s8, s16, s8
	s_addc_u32 s9, s17, s9
	s_lshl_b32 s13, s11, 8
	s_add_u32 s8, s8, s13
	s_addc_u32 s9, s9, 0
	v_lshl_add_u64 v[2:3], s[8:9], 0, v[180:181]
	v_lshl_add_u64 v[2:3], v[2:3], 0, v[0:1]
	s_barrier
	global_load_dwordx4 v[66:69], v[2:3], off offset:160
	global_load_dwordx4 v[70:73], v[2:3], off offset:224
	global_load_dwordx4 v[92:95], v[2:3], off offset:128
	global_load_dwordx4 v[98:101], v[2:3], off offset:192
	global_load_dwordx4 v[108:111], v[2:3], off offset:32
	global_load_dwordx4 v[112:115], v[2:3], off offset:96
	global_load_dwordx4 v[116:119], v[2:3], off
	global_load_dwordx4 v[120:123], v[2:3], off offset:64
	global_load_dwordx4 v[58:61], v[182:183], off
	global_load_dwordx4 v[62:65], v[182:183], off offset:16
	global_load_dwordx4 v[50:53], v[182:183], off offset:64
	global_load_dwordx4 v[54:57], v[182:183], off offset:80
	global_load_dwordx4 v[42:45], v[182:183], off offset:128
	global_load_dwordx4 v[46:49], v[182:183], off offset:144
	global_load_dwordx4 v[34:37], v[182:183], off offset:192
	global_load_dwordx4 v[38:41], v[182:183], off offset:208
	global_load_dwordx4 v[26:29], v[182:183], off offset:256
	global_load_dwordx4 v[30:33], v[182:183], off offset:272
	global_load_dwordx4 v[18:21], v[182:183], off offset:336
	global_load_dwordx4 v[22:25], v[182:183], off offset:320
	global_load_dwordx4 v[10:13], v[182:183], off offset:384
	global_load_dwordx4 v[14:17], v[182:183], off offset:400
	global_load_dwordx4 v[2:5], v[182:183], off offset:464
	global_load_dwordx4 v[6:9], v[182:183], off offset:448
	s_cmp_lt_i32 s12, 0
	s_waitcnt vmcnt(23)
	v_and_b32_e32 v79, 0xffff0000, v67
	s_waitcnt vmcnt(22)
	v_and_b32_e32 v75, 0xffff0000, v71
	v_lshlrev_b32_e32 v74, 16, v71
	v_and_b32_e32 v77, 0xffff0000, v70
	v_lshlrev_b32_e32 v76, 16, v70
	s_waitcnt vmcnt(19)
	v_and_b32_e32 v127, 0xffff0000, v108
	s_waitcnt vmcnt(17)
	v_and_b32_e32 v71, 0xffff0000, v116
	v_lshlrev_b32_e32 v126, 16, v108
	v_lshlrev_b32_e32 v70, 16, v116
	v_mul_f32_e32 v108, v71, v71
	v_lshlrev_b32_e32 v78, 16, v67
	v_and_b32_e32 v83, 0xffff0000, v66
	v_lshlrev_b32_e32 v82, 16, v66
	v_and_b32_e32 v125, 0xffff0000, v109
	v_lshlrev_b32_e32 v124, 16, v109
	v_and_b32_e32 v131, 0xffff0000, v119
	v_lshlrev_b32_e32 v130, 16, v119
	s_waitcnt vmcnt(16)
	v_and_b32_e32 v133, 0xffff0000, v123
	v_lshlrev_b32_e32 v132, 16, v123
	v_and_b32_e32 v67, 0xffff0000, v118
	v_lshlrev_b32_e32 v66, 16, v118
	v_and_b32_e32 v119, 0xffff0000, v122
	v_lshlrev_b32_e32 v118, 16, v122
	v_and_b32_e32 v123, 0xffff0000, v117
	v_lshlrev_b32_e32 v122, 16, v117
	v_pk_fma_f32 v[108:109], v[70:71], v[70:71], v[108:109] op_sel_hi:[1,1,0]
	v_and_b32_e32 v107, 0xffff0000, v110
	v_lshlrev_b32_e32 v106, 16, v110
	v_pk_fma_f32 v[108:109], v[122:123], v[122:123], v[108:109]
	v_mul_f32_e32 v110, v123, v123
	v_pk_add_f32 v[108:109], v[110:111], v[108:109] op_sel_hi:[0,1]
	v_pk_fma_f32 v[108:109], v[66:67], v[66:67], v[108:109]
	v_mul_f32_e32 v110, v67, v67
	v_pk_add_f32 v[108:109], v[110:111], v[108:109] op_sel_hi:[0,1]
	v_pk_fma_f32 v[108:109], v[130:131], v[130:131], v[108:109]
	v_mul_f32_e32 v110, v131, v131
	v_pk_add_f32 v[108:109], v[110:111], v[108:109] op_sel_hi:[0,1]
	v_pk_fma_f32 v[108:109], v[126:127], v[126:127], v[108:109]
	v_mul_f32_e32 v110, v127, v127
	v_pk_add_f32 v[108:109], v[110:111], v[108:109] op_sel_hi:[0,1]
	v_pk_fma_f32 v[108:109], v[124:125], v[124:125], v[108:109]
	v_mul_f32_e32 v110, v125, v125
	v_pk_add_f32 v[108:109], v[110:111], v[108:109] op_sel_hi:[0,1]
	v_pk_fma_f32 v[108:109], v[106:107], v[106:107], v[108:109]
	v_mul_f32_e32 v110, v107, v107
	v_and_b32_e32 v81, 0xffff0000, v101
	v_lshlrev_b32_e32 v80, 16, v101
	v_and_b32_e32 v85, 0xffff0000, v100
	v_lshlrev_b32_e32 v84, 16, v100
	v_and_b32_e32 v101, 0xffff0000, v111
	v_lshlrev_b32_e32 v100, 16, v111
	v_pk_add_f32 v[108:109], v[110:111], v[108:109] op_sel_hi:[0,1]
	v_pk_fma_f32 v[108:109], v[100:101], v[100:101], v[108:109]
	v_mul_f32_e32 v110, v101, v101
	v_and_b32_e32 v135, 0xffff0000, v121
	v_lshlrev_b32_e32 v134, 16, v121
	v_and_b32_e32 v121, 0xffff0000, v120
	v_lshlrev_b32_e32 v120, 16, v120
	v_pk_add_f32 v[108:109], v[110:111], v[108:109] op_sel_hi:[0,1]
	v_pk_fma_f32 v[108:109], v[120:121], v[120:121], v[108:109]
	v_mul_f32_e32 v110, v121, v121
	v_pk_add_f32 v[108:109], v[110:111], v[108:109] op_sel_hi:[0,1]
	v_pk_fma_f32 v[108:109], v[134:135], v[134:135], v[108:109]
	v_mul_f32_e32 v110, v135, v135
	v_pk_add_f32 v[108:109], v[110:111], v[108:109] op_sel_hi:[0,1]
	v_pk_fma_f32 v[108:109], v[118:119], v[118:119], v[108:109]
	v_mul_f32_e32 v110, v119, v119
	v_pk_add_f32 v[108:109], v[110:111], v[108:109] op_sel_hi:[0,1]
	v_pk_fma_f32 v[108:109], v[132:133], v[132:133], v[108:109]
	v_mul_f32_e32 v110, v133, v133
	v_and_b32_e32 v129, 0xffff0000, v112
	v_lshlrev_b32_e32 v128, 16, v112
	v_pk_add_f32 v[108:109], v[110:111], v[108:109] op_sel_hi:[0,1]
	v_pk_fma_f32 v[108:109], v[128:129], v[128:129], v[108:109]
	v_mul_f32_e32 v110, v129, v129
	v_and_b32_e32 v105, 0xffff0000, v113
	v_lshlrev_b32_e32 v104, 16, v113
	v_pk_add_f32 v[108:109], v[110:111], v[108:109] op_sel_hi:[0,1]
	v_pk_fma_f32 v[108:109], v[104:105], v[104:105], v[108:109]
	v_mul_f32_e32 v110, v105, v105
	v_and_b32_e32 v103, 0xffff0000, v114
	v_lshlrev_b32_e32 v102, 16, v114
	v_pk_add_f32 v[108:109], v[110:111], v[108:109] op_sel_hi:[0,1]
	v_pk_fma_f32 v[108:109], v[102:103], v[102:103], v[108:109]
	v_mul_f32_e32 v110, v103, v103
	v_and_b32_e32 v87, 0xffff0000, v95
	v_lshlrev_b32_e32 v86, 16, v95
	v_and_b32_e32 v91, 0xffff0000, v94
	v_lshlrev_b32_e32 v90, 16, v94
	v_and_b32_e32 v95, 0xffff0000, v93
	v_lshlrev_b32_e32 v94, 16, v93
	v_and_b32_e32 v89, 0xffff0000, v99
	v_lshlrev_b32_e32 v88, 16, v99
	v_and_b32_e32 v97, 0xffff0000, v92
	v_lshlrev_b32_e32 v96, 16, v92
	v_and_b32_e32 v93, 0xffff0000, v98
	v_lshlrev_b32_e32 v92, 16, v98
	v_and_b32_e32 v99, 0xffff0000, v115
	v_lshlrev_b32_e32 v98, 16, v115
	v_pk_add_f32 v[108:109], v[110:111], v[108:109] op_sel_hi:[0,1]
	v_pk_fma_f32 v[108:109], v[98:99], v[98:99], v[108:109]
	v_mul_f32_e32 v110, v99, v99
	v_pk_add_f32 v[108:109], v[110:111], v[108:109] op_sel_hi:[0,1]
	v_pk_fma_f32 v[108:109], v[96:97], v[96:97], v[108:109]
	v_mul_f32_e32 v110, v97, v97
	v_pk_add_f32 v[108:109], v[110:111], v[108:109] op_sel_hi:[0,1]
	v_pk_fma_f32 v[108:109], v[94:95], v[94:95], v[108:109]
	v_mul_f32_e32 v110, v95, v95
	v_pk_add_f32 v[108:109], v[110:111], v[108:109] op_sel_hi:[0,1]
	v_pk_fma_f32 v[108:109], v[90:91], v[90:91], v[108:109]
	v_mul_f32_e32 v110, v91, v91
	v_pk_add_f32 v[108:109], v[110:111], v[108:109] op_sel_hi:[0,1]
	v_pk_fma_f32 v[108:109], v[86:87], v[86:87], v[108:109]
	v_mul_f32_e32 v110, v87, v87
	v_pk_add_f32 v[108:109], v[110:111], v[108:109] op_sel_hi:[0,1]
	v_pk_fma_f32 v[108:109], v[82:83], v[82:83], v[108:109]
	v_mul_f32_e32 v110, v83, v83
	v_pk_add_f32 v[108:109], v[110:111], v[108:109] op_sel_hi:[0,1]
	v_pk_fma_f32 v[108:109], v[78:79], v[78:79], v[108:109]
	v_mul_f32_e32 v110, v79, v79
	v_pk_add_f32 v[112:113], v[110:111], v[108:109] op_sel_hi:[0,1]
	v_and_b32_e32 v111, 0xffff0000, v72
	v_lshlrev_b32_e32 v110, 16, v68
	v_and_b32_e32 v109, 0xffff0000, v68
	v_pk_fma_f32 v[112:113], v[110:111], v[110:111], v[112:113]
	v_mul_f32_e32 v68, v109, v109
	v_pk_add_f32 v[136:137], v[68:69], v[112:113] op_sel_hi:[0,1]
	v_and_b32_e32 v115, 0xffff0000, v73
	v_lshlrev_b32_e32 v114, 16, v69
	v_and_b32_e32 v113, 0xffff0000, v69
	v_lshlrev_b32_e32 v108, 16, v72
	v_lshlrev_b32_e32 v112, 16, v73
	v_pk_fma_f32 v[72:73], v[114:115], v[114:115], v[136:137]
	v_mul_f32_e32 v136, v113, v113
	v_pk_add_f32 v[72:73], v[136:137], v[72:73] op_sel_hi:[0,1]
	v_pk_fma_f32 v[72:73], v[92:93], v[92:93], v[72:73]
	v_mul_f32_e32 v136, v93, v93
	v_pk_add_f32 v[72:73], v[136:137], v[72:73] op_sel_hi:[0,1]
	v_pk_fma_f32 v[72:73], v[88:89], v[88:89], v[72:73]
	v_mul_f32_e32 v136, v89, v89
	v_pk_add_f32 v[72:73], v[136:137], v[72:73] op_sel_hi:[0,1]
	v_pk_fma_f32 v[72:73], v[84:85], v[84:85], v[72:73]
	v_mul_f32_e32 v136, v85, v85
	v_pk_add_f32 v[72:73], v[136:137], v[72:73] op_sel_hi:[0,1]
	v_pk_fma_f32 v[72:73], v[80:81], v[80:81], v[72:73]
	v_mul_f32_e32 v136, v81, v81
	v_pk_add_f32 v[72:73], v[136:137], v[72:73] op_sel_hi:[0,1]
	v_pk_fma_f32 v[72:73], v[76:77], v[76:77], v[72:73]
	v_mul_f32_e32 v136, v77, v77
	v_pk_add_f32 v[72:73], v[136:137], v[72:73] op_sel_hi:[0,1]
	v_pk_mov_b32 v[116:117], v[110:111], v[108:109] op_sel:[1,0]
	v_pk_fma_f32 v[72:73], v[74:75], v[74:75], v[72:73]
	v_mul_f32_e32 v136, v75, v75
	v_pk_add_f32 v[72:73], v[136:137], v[72:73] op_sel_hi:[0,1]
	v_mul_f32_e32 v136, v117, v117
	v_pk_mov_b32 v[68:69], v[114:115], v[112:113] op_sel:[1,0]
	v_pk_add_f32 v[72:73], v[136:137], v[72:73] op_sel_hi:[0,1]
	v_pk_fma_f32 v[72:73], v[116:117], v[116:117], v[72:73]
	v_mul_f32_e32 v116, v69, v69
	v_pk_add_f32 v[72:73], v[116:117], v[72:73] op_sel_hi:[0,1]
	v_pk_fma_f32 v[68:69], v[68:69], v[68:69], v[72:73]
	s_waitcnt vmcnt(5)
	v_mov_b32_e32 v136, v18
	v_mov_b32_e32 v69, v68
	s_nop 1
	v_permlane32_swap_b32_e32 v68, v69
	v_add_f32_e32 v68, v68, v69
	v_fmamk_f32 v68, v68, 0x3c000000, v204
	v_mul_f32_e32 v69, 0x4b800000, v68
	v_cmp_gt_f32_e32 vcc, s49, v68
	s_waitcnt vmcnt(1)
	v_mov_b32_e32 v18, v2
	v_mov_b32_e32 v137, v3
	v_cndmask_b32_e32 v68, v68, v69, vcc
	v_rsq_f32_e32 v68, v68
	s_nop 0
	v_mul_f32_e32 v69, 0x45800000, v68
	v_cndmask_b32_e32 v68, v68, v69, vcc
	v_mul_f32_e32 v116, 0x3e0293ee, v68
	v_pk_mul_f32 v[58:59], v[58:59], v[116:117] op_sel_hi:[1,0]
	v_pk_mul_f32 v[62:63], v[62:63], v[116:117] op_sel_hi:[1,0]
	v_pk_mul_f32 v[70:71], v[58:59], v[70:71]
	v_pk_mul_f32 v[58:59], v[60:61], v[116:117] op_sel_hi:[1,0]
	v_pk_mul_f32 v[50:51], v[50:51], v[116:117] op_sel_hi:[1,0]
	v_pk_mul_f32 v[54:55], v[54:55], v[116:117] op_sel_hi:[1,0]
	v_pk_mul_f32 v[42:43], v[42:43], v[116:117] op_sel_hi:[1,0]
	v_pk_mul_f32 v[66:67], v[62:63], v[66:67]
	v_pk_mul_f32 v[72:73], v[58:59], v[122:123]
	v_pk_mul_f32 v[62:63], v[50:51], v[126:127]
	v_pk_mul_f32 v[58:59], v[54:55], v[106:107]
	v_pk_mul_f32 v[50:51], v[52:53], v[116:117] op_sel_hi:[1,0]
	v_pk_mul_f32 v[46:47], v[46:47], v[116:117] op_sel_hi:[1,0]
	v_pk_mul_f32 v[54:55], v[42:43], v[120:121]
	v_pk_mul_f32 v[42:43], v[44:45], v[116:117] op_sel_hi:[1,0]
	v_pk_mul_f32 v[34:35], v[34:35], v[116:117] op_sel_hi:[1,0]
	v_pk_mul_f32 v[38:39], v[38:39], v[116:117] op_sel_hi:[1,0]
	v_pk_mul_f32 v[26:27], v[26:27], v[116:117] op_sel_hi:[1,0]
	v_pk_mul_f32 v[60:61], v[64:65], v[116:117] op_sel_hi:[1,0]
	v_pk_mul_f32 v[52:53], v[56:57], v[116:117] op_sel_hi:[1,0]
	v_pk_mul_f32 v[64:65], v[50:51], v[124:125]
	v_pk_mul_f32 v[50:51], v[46:47], v[118:119]
	v_pk_mul_f32 v[56:57], v[42:43], v[134:135]
	v_pk_mul_f32 v[46:47], v[34:35], v[128:129]
	v_pk_mul_f32 v[42:43], v[38:39], v[102:103]
	v_pk_mul_f32 v[34:35], v[36:37], v[116:117] op_sel_hi:[1,0]
	v_pk_mul_f32 v[30:31], v[116:117], v[30:31] op_sel_hi:[0,1]
	v_pk_mul_f32 v[38:39], v[26:27], v[96:97]
	v_pk_mul_f32 v[26:27], v[28:29], v[116:117] op_sel_hi:[1,0]
	v_pk_mul_f32 v[22:23], v[116:117], v[22:23] op_sel_hi:[0,1]
	v_pk_mul_f32 v[10:11], v[116:117], v[10:11] op_sel_hi:[0,1]
	v_pk_mul_f32 v[44:45], v[48:49], v[116:117] op_sel_hi:[1,0]
	v_pk_mul_f32 v[36:37], v[40:41], v[116:117] op_sel_hi:[1,0]
	v_pk_mul_f32 v[48:49], v[34:35], v[104:105]
	v_pk_mul_f32 v[34:35], v[30:31], v[90:91]
	v_pk_mul_f32 v[28:29], v[116:117], v[32:33] op_sel_hi:[0,1]
	v_pk_mul_f32 v[40:41], v[26:27], v[94:95]
	v_pk_mul_f32 v[30:31], v[22:23], v[82:83]
	v_pk_mul_f32 v[18:19], v[116:117], v[18:19] op_sel_hi:[0,1]
	v_pk_mul_f32 v[22:23], v[116:117], v[24:25] op_sel_hi:[0,1]
	v_mov_b32_e32 v24, v20
	v_mov_b32_e32 v25, v5
	v_mov_b32_e32 v20, v4
	v_pk_mul_f32 v[26:27], v[10:11], v[92:93]
	v_pk_mul_f32 v[10:11], v[116:117], v[12:13] op_sel_hi:[0,1]
	v_pk_mul_f32 v[12:13], v[116:117], v[16:17] op_sel_hi:[0,1]
	s_waitcnt vmcnt(0)
	v_pk_mul_f32 v[6:7], v[116:117], v[6:7] op_sel_hi:[0,1]
	v_pk_mul_f32 v[32:33], v[28:29], v[86:87]
	v_pk_mul_f32 v[86:87], v[116:117], v[136:137] op_sel_hi:[0,1]
	v_pk_mul_f32 v[82:83], v[116:117], v[24:25] op_sel_hi:[0,1]
	v_pk_mul_f32 v[20:21], v[116:117], v[20:21] op_sel_hi:[0,1]
	v_pk_mul_f32 v[14:15], v[116:117], v[14:15] op_sel_hi:[0,1]
	v_pk_mul_f32 v[24:25], v[12:13], v[80:81]
	v_pk_mul_f32 v[80:81], v[18:19], v[108:109]
	v_pk_mul_f32 v[18:19], v[6:7], v[76:77]
	v_pk_mul_f32 v[6:7], v[116:117], v[8:9] op_sel_hi:[0,1]
	v_pk_mul_f32 v[68:69], v[60:61], v[130:131]
	v_pk_mul_f32 v[60:61], v[52:53], v[100:101]
	v_pk_mul_f32 v[52:53], v[44:45], v[132:133]
	v_pk_mul_f32 v[44:45], v[36:37], v[98:99]
	v_pk_mul_f32 v[36:37], v[22:23], v[78:79]
	v_pk_mul_f32 v[22:23], v[14:15], v[84:85]
	v_pk_mul_f32 v[28:29], v[10:11], v[88:89]
	v_pk_mul_f32 v[78:79], v[86:87], v[110:111]
	v_pk_mul_f32 v[76:77], v[20:21], v[112:113]
	v_pk_mul_f32 v[20:21], v[6:7], v[74:75]
	v_pk_mul_f32 v[74:75], v[82:83], v[114:115]
	s_cbranch_scc1 .LBB0_284
	v_add_u32_e32 v90, s12, v221
	v_ashrrev_i32_e32 v2, 1, v90
	v_and_b32_e32 v2, 0xffffffe0, v2
	v_ashrrev_i32_e32 v3, 31, v2
	v_lshl_add_u64 v[86:87], v[2:3], 3, v[192:193]
	global_load_dwordx4 v[2:5], v[86:87], off offset:48
	global_load_dwordx4 v[6:9], v[86:87], off offset:32
	global_load_dwordx4 v[10:13], v[86:87], off offset:16
	global_load_dwordx4 v[14:17], v[86:87], off
	v_pk_mov_b32 v[84:85], v[80:81], v[78:79] op_sel:[1,0]
	v_pk_mov_b32 v[82:83], v[76:77], v[74:75] op_sel:[1,0]
	s_waitcnt vmcnt(0)
	v_mov_b32_e32 v89, v16
	v_mov_b32_e32 v16, v15
	v_mov_b32_e32 v88, v14
	v_pk_mul_f32 v[14:15], v[70:71], v[16:17]
	v_pk_mul_f32 v[16:17], v[54:55], v[16:17]
	v_pk_fma_f32 v[54:55], v[54:55], v[88:89], v[14:15]
	v_mov_b32_e32 v15, v12
	v_mov_b32_e32 v12, v11
	v_mov_b32_e32 v14, v10
	v_pk_mul_f32 v[10:11], v[72:73], v[12:13]
	v_pk_mul_f32 v[12:13], v[56:57], v[12:13]
	v_pk_fma_f32 v[56:57], v[56:57], v[14:15], v[10:11]
	v_mov_b32_e32 v11, v8
	v_mov_b32_e32 v8, v7
	v_mov_b32_e32 v10, v6
	v_pk_mul_f32 v[6:7], v[66:67], v[8:9]
	v_pk_mul_f32 v[8:9], v[50:51], v[8:9]
	v_pk_fma_f32 v[50:51], v[50:51], v[10:11], v[6:7]
	v_mov_b32_e32 v7, v4
	v_mov_b32_e32 v4, v3
	v_mov_b32_e32 v6, v2
	v_pk_mul_f32 v[2:3], v[68:69], v[4:5]
	v_pk_mul_f32 v[4:5], v[52:53], v[4:5]
	v_pk_fma_f32 v[70:71], v[70:71], v[88:89], v[16:17] neg_lo:[0,0,1] neg_hi:[0,0,1]
	v_pk_fma_f32 v[72:73], v[72:73], v[14:15], v[12:13] neg_lo:[0,0,1] neg_hi:[0,0,1]
	v_pk_fma_f32 v[66:67], v[66:67], v[10:11], v[8:9] neg_lo:[0,0,1] neg_hi:[0,0,1]
	v_pk_fma_f32 v[68:69], v[68:69], v[6:7], v[4:5] neg_lo:[0,0,1] neg_hi:[0,0,1]
	v_pk_fma_f32 v[52:53], v[52:53], v[6:7], v[2:3]
	global_load_dwordx4 v[2:5], v[86:87], off offset:176
	global_load_dwordx4 v[6:9], v[86:87], off offset:160
	global_load_dwordx4 v[10:13], v[86:87], off offset:144
	global_load_dwordx4 v[14:17], v[86:87], off offset:128
	s_waitcnt vmcnt(0)
	v_mov_b32_e32 v87, v16
	v_mov_b32_e32 v16, v15
	v_mov_b32_e32 v86, v14
	v_pk_mul_f32 v[14:15], v[62:63], v[16:17]
	v_pk_mul_f32 v[16:17], v[46:47], v[16:17]
	v_pk_fma_f32 v[46:47], v[46:47], v[86:87], v[14:15]
	v_mov_b32_e32 v15, v12
	v_mov_b32_e32 v12, v11
	v_mov_b32_e32 v14, v10
	v_pk_mul_f32 v[10:11], v[64:65], v[12:13]
	v_pk_mul_f32 v[12:13], v[48:49], v[12:13]
	v_pk_fma_f32 v[48:49], v[48:49], v[14:15], v[10:11]
	v_mov_b32_e32 v11, v8
	v_mov_b32_e32 v8, v7
	v_mov_b32_e32 v10, v6
	v_pk_mul_f32 v[6:7], v[58:59], v[8:9]
	v_pk_mul_f32 v[8:9], v[42:43], v[8:9]
	v_pk_fma_f32 v[42:43], v[42:43], v[10:11], v[6:7]
	v_mov_b32_e32 v7, v4
	v_mov_b32_e32 v4, v3
	v_mov_b32_e32 v6, v2
	v_pk_mul_f32 v[2:3], v[60:61], v[4:5]
	v_pk_mul_f32 v[4:5], v[44:45], v[4:5]
	v_pk_fma_f32 v[44:45], v[44:45], v[6:7], v[2:3]
	v_lshlrev_b32_e32 v2, 8, v90
	v_and_b32_e32 v2, 0x3f00, v2
	v_mov_b32_e32 v3, v1
	v_pk_fma_f32 v[62:63], v[62:63], v[86:87], v[16:17] neg_lo:[0,0,1] neg_hi:[0,0,1]
	v_lshl_add_u64 v[86:87], v[192:193], 0, v[2:3]
	v_pk_fma_f32 v[64:65], v[64:65], v[14:15], v[12:13] neg_lo:[0,0,1] neg_hi:[0,0,1]
	v_pk_fma_f32 v[58:59], v[58:59], v[10:11], v[8:9] neg_lo:[0,0,1] neg_hi:[0,0,1]
	v_pk_fma_f32 v[60:61], v[60:61], v[6:7], v[4:5] neg_lo:[0,0,1] neg_hi:[0,0,1]
	global_load_dwordx4 v[2:5], v[86:87], off offset:48
	global_load_dwordx4 v[6:9], v[86:87], off offset:32
	global_load_dwordx4 v[10:13], v[86:87], off offset:16
	global_load_dwordx4 v[14:17], v[86:87], off
	s_waitcnt vmcnt(0)
	v_mov_b32_e32 v89, v16
	v_mov_b32_e32 v16, v15
	v_mov_b32_e32 v88, v14
	v_pk_mul_f32 v[14:15], v[38:39], v[16:17]
	v_pk_mul_f32 v[16:17], v[26:27], v[16:17]
	v_pk_fma_f32 v[26:27], v[26:27], v[88:89], v[14:15]
	v_mov_b32_e32 v15, v12
	v_mov_b32_e32 v12, v11
	v_mov_b32_e32 v14, v10
	v_pk_mul_f32 v[10:11], v[40:41], v[12:13]
	v_pk_mul_f32 v[12:13], v[28:29], v[12:13]
	v_pk_fma_f32 v[28:29], v[28:29], v[14:15], v[10:11]
	v_mov_b32_e32 v11, v8
	v_mov_b32_e32 v8, v7
	v_mov_b32_e32 v10, v6
	v_pk_mul_f32 v[6:7], v[34:35], v[8:9]
	v_pk_mul_f32 v[8:9], v[22:23], v[8:9]
	v_pk_fma_f32 v[22:23], v[22:23], v[10:11], v[6:7]
	v_mov_b32_e32 v7, v4
	v_mov_b32_e32 v4, v3
	v_mov_b32_e32 v6, v2
	v_pk_mul_f32 v[2:3], v[32:33], v[4:5]
	v_pk_mul_f32 v[4:5], v[24:25], v[4:5]
	v_pk_fma_f32 v[38:39], v[38:39], v[88:89], v[16:17] neg_lo:[0,0,1] neg_hi:[0,0,1]
	v_pk_fma_f32 v[40:41], v[40:41], v[14:15], v[12:13] neg_lo:[0,0,1] neg_hi:[0,0,1]
	v_pk_fma_f32 v[34:35], v[34:35], v[10:11], v[8:9] neg_lo:[0,0,1] neg_hi:[0,0,1]
	v_pk_fma_f32 v[32:33], v[32:33], v[6:7], v[4:5] neg_lo:[0,0,1] neg_hi:[0,0,1]
	v_pk_fma_f32 v[24:25], v[24:25], v[6:7], v[2:3]
	global_load_dwordx4 v[2:5], v[86:87], off offset:176
	global_load_dwordx4 v[6:9], v[86:87], off offset:160
	global_load_dwordx4 v[10:13], v[86:87], off offset:144
	global_load_dwordx4 v[14:17], v[86:87], off offset:128
	s_waitcnt vmcnt(3)
	v_mov_b32_e32 v88, v3
	s_waitcnt vmcnt(2)
	v_mov_b32_e32 v86, v7
	v_mov_b32_e32 v87, v8
	s_waitcnt vmcnt(0)
	v_mov_b32_e32 v91, v16
	v_mov_b32_e32 v16, v15
	v_mov_b32_e32 v90, v14
	v_pk_mul_f32 v[14:15], v[30:31], v[16:17]
	v_pk_mul_f32 v[16:17], v[18:19], v[16:17]
	v_pk_fma_f32 v[18:19], v[18:19], v[90:91], v[14:15]
	v_mov_b32_e32 v15, v12
	v_mov_b32_e32 v12, v11
	v_mov_b32_e32 v14, v10
	v_pk_mul_f32 v[10:11], v[36:37], v[12:13]
	v_pk_mul_f32 v[12:13], v[20:21], v[12:13]
	v_pk_fma_f32 v[20:21], v[20:21], v[14:15], v[10:11]
	v_pk_fma_f32 v[36:37], v[36:37], v[14:15], v[12:13] neg_lo:[0,0,1] neg_hi:[0,0,1]
	v_pk_mov_b32 v[14:15], v[86:87], v[86:87] op_sel:[1,0]
	v_mov_b32_e32 v7, v9
	v_pk_mov_b32 v[12:13], v[78:79], v[80:81] op_sel:[1,0]
	v_mov_b32_e32 v8, v9
	v_mov_b32_e32 v9, v15
	v_mov_b32_e32 v89, v4
	v_pk_mul_f32 v[8:9], v[12:13], v[8:9]
	v_mov_b32_e32 v15, v6
	v_pk_fma_f32 v[8:9], v[84:85], v[14:15], v[8:9] neg_lo:[0,0,1] neg_hi:[0,0,1]
	v_pk_mov_b32 v[14:15], v[88:89], v[88:89] op_sel:[1,0]
	v_mov_b32_e32 v3, v5
	v_pk_mov_b32 v[12:13], v[74:75], v[76:77] op_sel:[1,0]
	v_mov_b32_e32 v4, v5
	v_mov_b32_e32 v5, v15
	v_pk_mul_f32 v[10:11], v[80:81], v[6:7]
	v_pk_mul_f32 v[4:5], v[12:13], v[4:5]
	v_mov_b32_e32 v15, v2
	v_pk_fma_f32 v[6:7], v[78:79], v[86:87], v[10:11]
	v_pk_mul_f32 v[10:11], v[76:77], v[2:3]
	v_pk_fma_f32 v[4:5], v[82:83], v[14:15], v[4:5] neg_lo:[0,0,1] neg_hi:[0,0,1]
	v_pk_fma_f32 v[30:31], v[30:31], v[90:91], v[16:17] neg_lo:[0,0,1] neg_hi:[0,0,1]
	v_pk_fma_f32 v[2:3], v[74:75], v[88:89], v[10:11]
	v_mov_b32_e32 v77, v4
	v_mov_b32_e32 v74, v5
	v_mov_b32_e32 v81, v8
	v_mov_b32_e32 v78, v9
	s_branch .LBB0_285
